# P12 gate-up2 GEMM: epilogue column/row loads issued in last K-iteration instead of behind vmcnt(0) at epilogue head
# speedup vs baseline: 1.0059x; 1.0059x over previous
.LBB0_3265:
	ds_read_b128 v[130:133], v171
	ds_read_b128 v[134:137], v171 offset:1024
	ds_read_b128 v[138:141], v171 offset:2048
	ds_read_b128 v[142:145], v171 offset:3072
	s_add_u32 s18, s24, 0xfffc0080
	s_addc_u32 s19, s25, -1
	s_cmp_eq_u32 s63, 12
	s_cselect_b32 s19, s11, s19
	s_cselect_b32 s18, s57, s18
	s_cselect_b32 s35, s9, s62
	s_cselect_b32 s34, s60, s61
	s_cbranch_scc0 .Lp12_nopf
	s_ashr_i32 s68, s16, 3
	s_mul_hi_i32 s69, s68, 0x5800
	s_mulk_i32 s68, 0x5800
	s_add_u32 s68, s48, s68
	s_addc_u32 s69, s49, s69
	s_lshl_b32 s70, s17, 8
	s_ashr_i32 s71, s70, 31
	s_lshl_b64 s[70:71], s[70:71], 2
	s_add_u32 s66, s68, s70
	s_addc_u32 s67, s69, s71
	v_lshlrev_b32_e32 v248, 2, v156
	v_lshl_add_u32 v253, s16, 8, v1
	v_lshlrev_b32_e32 v253, 2, v253
	global_load_dwordx4 v[236:239], v248, s[66:67]
	global_load_dwordx4 v[240:243], v248, s[66:67] offset:512
	global_load_dwordx4 v[244:247], v248, s[66:67] offset:16
	global_load_dwordx4 v[248:251], v248, s[66:67] offset:528
	global_load_dword v228, v253, s[4:5]
	global_load_dword v229, v253, s[4:5] offset:64
	global_load_dword v233, v253, s[4:5] offset:128
	global_load_dword v234, v253, s[4:5] offset:192
	global_load_dword v235, v253, s[4:5] offset:512
	global_load_dword v252, v253, s[4:5] offset:576
	global_load_dword v176, v253, s[4:5] offset:640
	global_load_dword v172, v253, s[4:5] offset:704
.Lp12_nopf:
	v_lshl_add_u64 v[174:175], s[24:25], 0, v[158:159]
	s_add_i32 m0, s43, 0xc000
	ds_read_b128 v[166:169], v173
	ds_read_b128 v[178:181], v173 offset:1024
	ds_read_b128 v[182:185], v173 offset:2048
	ds_read_b128 v[186:189], v173 offset:3072
	ds_read_b128 v[190:193], v173 offset:4096
	ds_read_b128 v[194:197], v173 offset:5120
	ds_read_b128 v[198:201], v173 offset:6144
	ds_read_b128 v[202:205], v173 offset:7168
	global_load_lds_dwordx4 v[174:175], off
	v_lshl_add_u64 v[174:175], s[24:25], 0, v[160:161]
	s_add_i32 m0, s43, 0xe000
	s_nop 0
	global_load_lds_dwordx4 v[174:175], off
	s_waitcnt lgkmcnt(8)
	s_barrier
	s_waitcnt lgkmcnt(0)
	s_setprio 1
	s_waitcnt lgkmcnt(0)
	v_mfma_f32_16x16x32_bf16 v[126:129], v[130:133], v[166:169], v[126:129]
	v_mfma_f32_16x16x32_bf16 v[122:125], v[138:141], v[166:169], v[122:125]
	v_mfma_f32_16x16x32_bf16 v[110:113], v[130:133], v[182:185], v[110:113]
	v_mfma_f32_16x16x32_bf16 v[106:109], v[138:141], v[182:185], v[106:109]
	v_mfma_f32_16x16x32_bf16 v[94:97], v[130:133], v[190:193], v[94:97]
	v_mfma_f32_16x16x32_bf16 v[90:93], v[138:141], v[190:193], v[90:93]
	v_mfma_f32_16x16x32_bf16 v[78:81], v[130:133], v[198:201], v[78:81]
	v_mfma_f32_16x16x32_bf16 v[74:77], v[138:141], v[198:201], v[74:77]
	v_mfma_f32_16x16x32_bf16 v[126:129], v[134:137], v[178:181], v[126:129]
	v_mfma_f32_16x16x32_bf16 v[122:125], v[142:145], v[178:181], v[122:125]
	v_mfma_f32_16x16x32_bf16 v[110:113], v[134:137], v[186:189], v[110:113]
	v_mfma_f32_16x16x32_bf16 v[106:109], v[142:145], v[186:189], v[106:109]
	v_mfma_f32_16x16x32_bf16 v[94:97], v[134:137], v[194:197], v[94:97]
	v_mfma_f32_16x16x32_bf16 v[90:93], v[142:145], v[194:197], v[90:93]
	v_mfma_f32_16x16x32_bf16 v[78:81], v[134:137], v[202:205], v[78:81]
	v_mfma_f32_16x16x32_bf16 v[74:77], v[142:145], v[202:205], v[74:77]
	s_setprio 0
	s_barrier
	s_add_i32 s20, s54, s42
	v_lshl_add_u64 v[174:175], s[34:35], 0, v[150:151]
	s_mov_b32 m0, s20
	ds_read_b128 v[206:209], v177
	ds_read_b128 v[210:213], v177 offset:1024
	ds_read_b128 v[214:217], v177 offset:2048
	ds_read_b128 v[218:221], v177 offset:3072
	global_load_lds_dwordx4 v[174:175], off
	v_lshl_add_u64 v[222:223], s[34:35], 0, v[146:147]
	s_add_i32 m0, s20, 0x2000
	s_nop 0
	global_load_lds_dwordx4 v[222:223], off
	s_barrier
	s_waitcnt lgkmcnt(0)
	s_setprio 1
	s_waitcnt lgkmcnt(0)
	v_mfma_f32_16x16x32_bf16 v[118:121], v[206:209], v[166:169], v[118:121]
	v_mfma_f32_16x16x32_bf16 v[114:117], v[214:217], v[166:169], v[114:117]
	v_mfma_f32_16x16x32_bf16 v[102:105], v[206:209], v[182:185], v[102:105]
	v_mfma_f32_16x16x32_bf16 v[98:101], v[214:217], v[182:185], v[98:101]
	v_mfma_f32_16x16x32_bf16 v[86:89], v[206:209], v[190:193], v[86:89]
	v_mfma_f32_16x16x32_bf16 v[82:85], v[214:217], v[190:193], v[82:85]
	v_mfma_f32_16x16x32_bf16 v[70:73], v[206:209], v[198:201], v[70:73]
	v_mfma_f32_16x16x32_bf16 v[66:69], v[214:217], v[198:201], v[66:69]
	v_mfma_f32_16x16x32_bf16 v[118:121], v[210:213], v[178:181], v[118:121]
	v_mfma_f32_16x16x32_bf16 v[114:117], v[218:221], v[178:181], v[114:117]
	v_mfma_f32_16x16x32_bf16 v[102:105], v[210:213], v[186:189], v[102:105]
	v_mfma_f32_16x16x32_bf16 v[98:101], v[218:221], v[186:189], v[98:101]
	v_mfma_f32_16x16x32_bf16 v[86:89], v[210:213], v[194:197], v[86:89]
	v_mfma_f32_16x16x32_bf16 v[82:85], v[218:221], v[194:197], v[82:85]
	v_mfma_f32_16x16x32_bf16 v[70:73], v[210:213], v[202:205], v[70:73]
	v_mfma_f32_16x16x32_bf16 v[66:69], v[218:221], v[202:205], v[66:69]
	s_setprio 0
	s_mov_b32 m0, s43
	v_lshl_add_u64 v[224:225], s[18:19], 0, v[152:153]
	s_barrier
	ds_read_b128 v[166:169], v173 offset:16384
	ds_read_b128 v[178:181], v173 offset:17408
	ds_read_b128 v[182:185], v173 offset:18432
	ds_read_b128 v[186:189], v173 offset:19456
	ds_read_b128 v[190:193], v173 offset:20480
	ds_read_b128 v[194:197], v173 offset:21504
	ds_read_b128 v[198:201], v173 offset:22528
	ds_read_b128 v[202:205], v173 offset:23552
	global_load_lds_dwordx4 v[224:225], off
	v_lshl_add_u64 v[226:227], s[18:19], 0, v[148:149]
	s_mov_b32 m0, s44
	s_nop 0
	global_load_lds_dwordx4 v[226:227], off
	s_barrier
	s_waitcnt lgkmcnt(0)
	s_setprio 1
	s_waitcnt lgkmcnt(0)
	v_mfma_f32_16x16x32_bf16 v[62:65], v[130:133], v[166:169], v[62:65]
	v_mfma_f32_16x16x32_bf16 v[58:61], v[138:141], v[166:169], v[58:61]
	v_mfma_f32_16x16x32_bf16 v[46:49], v[130:133], v[182:185], v[46:49]
	v_mfma_f32_16x16x32_bf16 v[42:45], v[138:141], v[182:185], v[42:45]
	v_mfma_f32_16x16x32_bf16 v[30:33], v[130:133], v[190:193], v[30:33]
	v_mfma_f32_16x16x32_bf16 v[26:29], v[138:141], v[190:193], v[26:29]
	v_mfma_f32_16x16x32_bf16 v[14:17], v[130:133], v[198:201], v[14:17]
	v_mfma_f32_16x16x32_bf16 v[10:13], v[138:141], v[198:201], v[10:13]
	v_mfma_f32_16x16x32_bf16 v[62:65], v[134:137], v[178:181], v[62:65]
	v_mfma_f32_16x16x32_bf16 v[58:61], v[142:145], v[178:181], v[58:61]
	v_mfma_f32_16x16x32_bf16 v[46:49], v[134:137], v[186:189], v[46:49]
	v_mfma_f32_16x16x32_bf16 v[42:45], v[142:145], v[186:189], v[42:45]
	v_mfma_f32_16x16x32_bf16 v[30:33], v[134:137], v[194:197], v[30:33]
	v_mfma_f32_16x16x32_bf16 v[26:29], v[142:145], v[194:197], v[26:29]
	v_mfma_f32_16x16x32_bf16 v[14:17], v[134:137], v[202:205], v[14:17]
	v_mfma_f32_16x16x32_bf16 v[10:13], v[142:145], v[202:205], v[10:13]
	s_setprio 0
	s_barrier
	s_add_u32 s20, s34, 0x40000
	s_addc_u32 s21, s35, 0
	s_add_i32 s64, s55, s42
	v_lshl_add_u64 v[130:131], s[20:21], 0, v[150:151]
	s_mov_b32 m0, s64
	s_nop 0
	global_load_lds_dwordx4 v[130:131], off
	v_lshl_add_u64 v[130:131], s[20:21], 0, v[146:147]
	s_add_i32 m0, s64, 0x2000
	s_nop 0
	global_load_lds_dwordx4 v[130:131], off
	s_waitcnt vmcnt(6)
	s_barrier
	s_setprio 1
	v_mfma_f32_16x16x32_bf16 v[54:57], v[206:209], v[166:169], v[54:57]
	v_mfma_f32_16x16x32_bf16 v[50:53], v[214:217], v[166:169], v[50:53]
	v_mfma_f32_16x16x32_bf16 v[38:41], v[206:209], v[182:185], v[38:41]
	v_mfma_f32_16x16x32_bf16 v[34:37], v[214:217], v[182:185], v[34:37]
	v_mfma_f32_16x16x32_bf16 v[22:25], v[206:209], v[190:193], v[22:25]
	v_mfma_f32_16x16x32_bf16 v[18:21], v[214:217], v[190:193], v[18:21]
	v_mfma_f32_16x16x32_bf16 v[6:9], v[206:209], v[198:201], v[6:9]
	v_mfma_f32_16x16x32_bf16 v[2:5], v[214:217], v[198:201], v[2:5]
	v_mfma_f32_16x16x32_bf16 v[54:57], v[210:213], v[178:181], v[54:57]
	v_mfma_f32_16x16x32_bf16 v[50:53], v[218:221], v[178:181], v[50:53]
	v_mfma_f32_16x16x32_bf16 v[38:41], v[210:213], v[186:189], v[38:41]
	v_mfma_f32_16x16x32_bf16 v[34:37], v[218:221], v[186:189], v[34:37]
	v_mfma_f32_16x16x32_bf16 v[22:25], v[210:213], v[194:197], v[22:25]
	v_mfma_f32_16x16x32_bf16 v[18:21], v[218:221], v[194:197], v[18:21]
	v_mfma_f32_16x16x32_bf16 v[6:9], v[210:213], v[202:205], v[6:9]
	v_mfma_f32_16x16x32_bf16 v[2:5], v[218:221], v[202:205], v[2:5]
	s_setprio 0
	s_add_i32 s20, 0, 0x18000
	v_add_u32_e32 v142, s20, v157
	s_barrier
	ds_read_b128 v[130:133], v142
	ds_read_b128 v[134:137], v142 offset:1024
	ds_read_b128 v[138:141], v142 offset:2048
	ds_read_b128 v[142:145], v142 offset:3072
	s_add_u32 s18, s18, 0x40000
	s_addc_u32 s19, s19, 0
	s_mov_b32 m0, s45
	v_lshl_add_u64 v[206:207], s[18:19], 0, v[152:153]
	ds_read_b128 v[166:169], v173 offset:32768
	ds_read_b128 v[178:181], v173 offset:33792
	ds_read_b128 v[182:185], v173 offset:34816
	ds_read_b128 v[186:189], v173 offset:35840
	ds_read_b128 v[190:193], v173 offset:36864
	ds_read_b128 v[194:197], v173 offset:37888
	ds_read_b128 v[198:201], v173 offset:38912
	ds_read_b128 v[202:205], v173 offset:39936
	global_load_lds_dwordx4 v[206:207], off
	v_lshl_add_u64 v[206:207], s[18:19], 0, v[148:149]
	s_mov_b32 m0, s46
	s_nop 0
	global_load_lds_dwordx4 v[206:207], off
	s_waitcnt lgkmcnt(8)
	s_barrier
	s_waitcnt lgkmcnt(0)
	s_setprio 1
	s_waitcnt lgkmcnt(0)
	v_mfma_f32_16x16x32_bf16 v[126:129], v[130:133], v[166:169], v[126:129]
	v_mfma_f32_16x16x32_bf16 v[122:125], v[138:141], v[166:169], v[122:125]
	v_mfma_f32_16x16x32_bf16 v[110:113], v[130:133], v[182:185], v[110:113]
	v_mfma_f32_16x16x32_bf16 v[106:109], v[138:141], v[182:185], v[106:109]
	v_mfma_f32_16x16x32_bf16 v[94:97], v[130:133], v[190:193], v[94:97]
	v_mfma_f32_16x16x32_bf16 v[90:93], v[138:141], v[190:193], v[90:93]
	v_mfma_f32_16x16x32_bf16 v[78:81], v[130:133], v[198:201], v[78:81]
	v_mfma_f32_16x16x32_bf16 v[74:77], v[138:141], v[198:201], v[74:77]
	v_mfma_f32_16x16x32_bf16 v[126:129], v[134:137], v[178:181], v[126:129]
	v_mfma_f32_16x16x32_bf16 v[122:125], v[142:145], v[178:181], v[122:125]
	v_mfma_f32_16x16x32_bf16 v[110:113], v[134:137], v[186:189], v[110:113]
	v_mfma_f32_16x16x32_bf16 v[106:109], v[142:145], v[186:189], v[106:109]
	v_mfma_f32_16x16x32_bf16 v[94:97], v[134:137], v[194:197], v[94:97]
	v_mfma_f32_16x16x32_bf16 v[90:93], v[142:145], v[194:197], v[90:93]
	v_mfma_f32_16x16x32_bf16 v[78:81], v[134:137], v[202:205], v[78:81]
	v_mfma_f32_16x16x32_bf16 v[74:77], v[142:145], v[202:205], v[74:77]
	s_setprio 0
	s_barrier
	s_add_i32 s21, 0, 0x1c000
	s_add_i32 s18, s20, s42
	v_add_u32_e32 v154, s21, v157
	v_lshl_add_u64 v[174:175], v[174:175], 0, s[6:7]
	s_mov_b32 m0, s18
	ds_read_b128 v[206:209], v154
	ds_read_b128 v[210:213], v154 offset:1024
	ds_read_b128 v[214:217], v154 offset:2048
	ds_read_b128 v[218:221], v154 offset:3072
	global_load_lds_dwordx4 v[174:175], off
	v_lshl_add_u64 v[174:175], v[222:223], 0, s[6:7]
	s_add_i32 m0, s18, 0x2000
	s_nop 0
	global_load_lds_dwordx4 v[174:175], off
	s_barrier
	s_waitcnt lgkmcnt(0)
	s_setprio 1
	s_waitcnt lgkmcnt(0)
	v_mfma_f32_16x16x32_bf16 v[118:121], v[206:209], v[166:169], v[118:121]
	v_mfma_f32_16x16x32_bf16 v[114:117], v[214:217], v[166:169], v[114:117]
	v_mfma_f32_16x16x32_bf16 v[102:105], v[206:209], v[182:185], v[102:105]
	v_mfma_f32_16x16x32_bf16 v[98:101], v[214:217], v[182:185], v[98:101]
	v_mfma_f32_16x16x32_bf16 v[86:89], v[206:209], v[190:193], v[86:89]
	v_mfma_f32_16x16x32_bf16 v[82:85], v[214:217], v[190:193], v[82:85]
	v_mfma_f32_16x16x32_bf16 v[70:73], v[206:209], v[198:201], v[70:73]
	v_mfma_f32_16x16x32_bf16 v[66:69], v[214:217], v[198:201], v[66:69]
	v_mfma_f32_16x16x32_bf16 v[118:121], v[210:213], v[178:181], v[118:121]
	v_mfma_f32_16x16x32_bf16 v[114:117], v[218:221], v[178:181], v[114:117]
	v_mfma_f32_16x16x32_bf16 v[102:105], v[210:213], v[186:189], v[102:105]
	v_mfma_f32_16x16x32_bf16 v[98:101], v[218:221], v[186:189], v[98:101]
	v_mfma_f32_16x16x32_bf16 v[86:89], v[210:213], v[194:197], v[86:89]
	v_mfma_f32_16x16x32_bf16 v[82:85], v[218:221], v[194:197], v[82:85]
	v_mfma_f32_16x16x32_bf16 v[70:73], v[210:213], v[202:205], v[70:73]
	v_mfma_f32_16x16x32_bf16 v[66:69], v[218:221], v[202:205], v[66:69]
	s_setprio 0
	s_mov_b32 m0, s50
	v_lshl_add_u64 v[174:175], v[224:225], 0, s[6:7]
	s_barrier
	ds_read_b128 v[166:169], v173 offset:49152
	ds_read_b128 v[178:181], v173 offset:50176
	ds_read_b128 v[182:185], v173 offset:51200
	ds_read_b128 v[186:189], v173 offset:52224
	ds_read_b128 v[190:193], v173 offset:53248
	ds_read_b128 v[194:197], v173 offset:54272
	ds_read_b128 v[198:201], v173 offset:55296
	ds_read_b128 v[202:205], v173 offset:56320
	global_load_lds_dwordx4 v[174:175], off
	v_lshl_add_u64 v[174:175], v[226:227], 0, s[6:7]
	s_mov_b32 m0, s51
	s_nop 0
	global_load_lds_dwordx4 v[174:175], off
	s_barrier
	s_waitcnt lgkmcnt(0)
	s_setprio 1
	s_waitcnt lgkmcnt(0)
	v_mfma_f32_16x16x32_bf16 v[62:65], v[130:133], v[166:169], v[62:65]
	v_mfma_f32_16x16x32_bf16 v[58:61], v[138:141], v[166:169], v[58:61]
	v_mfma_f32_16x16x32_bf16 v[46:49], v[130:133], v[182:185], v[46:49]
	v_mfma_f32_16x16x32_bf16 v[42:45], v[138:141], v[182:185], v[42:45]
	v_mfma_f32_16x16x32_bf16 v[30:33], v[130:133], v[190:193], v[30:33]
	v_mfma_f32_16x16x32_bf16 v[26:29], v[138:141], v[190:193], v[26:29]
	v_mfma_f32_16x16x32_bf16 v[14:17], v[130:133], v[198:201], v[14:17]
	v_mfma_f32_16x16x32_bf16 v[10:13], v[138:141], v[198:201], v[10:13]
	v_mfma_f32_16x16x32_bf16 v[62:65], v[134:137], v[178:181], v[62:65]
	v_mfma_f32_16x16x32_bf16 v[58:61], v[142:145], v[178:181], v[58:61]
	v_mfma_f32_16x16x32_bf16 v[46:49], v[134:137], v[186:189], v[46:49]
	v_mfma_f32_16x16x32_bf16 v[42:45], v[142:145], v[186:189], v[42:45]
	v_mfma_f32_16x16x32_bf16 v[30:33], v[134:137], v[194:197], v[30:33]
	v_mfma_f32_16x16x32_bf16 v[26:29], v[142:145], v[194:197], v[26:29]
	v_mfma_f32_16x16x32_bf16 v[14:17], v[134:137], v[202:205], v[14:17]
	v_mfma_f32_16x16x32_bf16 v[10:13], v[142:145], v[202:205], v[10:13]
	s_setprio 0
	s_barrier
	s_add_u32 s18, s34, 0x40080
	s_addc_u32 s19, s35, 0
	s_add_i32 s20, s21, s42
	v_lshl_add_u64 v[130:131], s[18:19], 0, v[150:151]
	s_mov_b32 m0, s20
	s_nop 0
	global_load_lds_dwordx4 v[130:131], off
	v_lshl_add_u64 v[130:131], s[18:19], 0, v[146:147]
	s_add_i32 m0, s20, 0x2000
	s_nop 0
	global_load_lds_dwordx4 v[130:131], off
	s_waitcnt vmcnt(6)
	s_barrier
	s_setprio 1
	v_mfma_f32_16x16x32_bf16 v[54:57], v[206:209], v[166:169], v[54:57]
	v_mfma_f32_16x16x32_bf16 v[50:53], v[214:217], v[166:169], v[50:53]
	v_mfma_f32_16x16x32_bf16 v[38:41], v[206:209], v[182:185], v[38:41]
	v_mfma_f32_16x16x32_bf16 v[34:37], v[214:217], v[182:185], v[34:37]
	v_mfma_f32_16x16x32_bf16 v[22:25], v[206:209], v[190:193], v[22:25]
	v_mfma_f32_16x16x32_bf16 v[18:21], v[214:217], v[190:193], v[18:21]
	v_mfma_f32_16x16x32_bf16 v[6:9], v[206:209], v[198:201], v[6:9]
	v_mfma_f32_16x16x32_bf16 v[2:5], v[214:217], v[198:201], v[2:5]
	v_mfma_f32_16x16x32_bf16 v[54:57], v[210:213], v[178:181], v[54:57]
	v_mfma_f32_16x16x32_bf16 v[50:53], v[218:221], v[178:181], v[50:53]
	v_mfma_f32_16x16x32_bf16 v[38:41], v[210:213], v[186:189], v[38:41]
	v_mfma_f32_16x16x32_bf16 v[34:37], v[218:221], v[186:189], v[34:37]
	v_mfma_f32_16x16x32_bf16 v[22:25], v[210:213], v[194:197], v[22:25]
	v_mfma_f32_16x16x32_bf16 v[18:21], v[218:221], v[194:197], v[18:21]
	v_mfma_f32_16x16x32_bf16 v[6:9], v[210:213], v[202:205], v[6:9]
	v_mfma_f32_16x16x32_bf16 v[2:5], v[218:221], v[202:205], v[2:5]
	s_setprio 0
	s_add_i32 s63, s63, 2
	s_add_u32 s24, s24, 0x100
	s_addc_u32 s25, s25, 0
	s_add_u32 s61, s61, 0x100
	s_addc_u32 s62, s62, 0
	s_cmp_gt_u32 s63, 13
	s_barrier
	s_cbranch_scc0 .LBB0_3265
	s_ashr_i32 s9, s16, 3
	s_mul_hi_i32 s11, s9, 0x5800
	s_mulk_i32 s9, 0x5800
	s_add_u32 s9, s48, s9
	s_addc_u32 s11, s49, s11
	s_lshl_b32 s18, s17, 8
	s_ashr_i32 s19, s18, 31
	s_lshl_b64 s[18:19], s[18:19], 2
	v_lshl_add_u32 v180, s16, 8, v1
	s_add_u32 s18, s9, s18
	s_addc_u32 s19, s11, s19
	v_lshlrev_b32_e32 v130, 2, v156
	v_ashrrev_i32_e32 v181, 31, v180
	v_mov_b32_e32 v142, v236
	v_mov_b32_e32 v143, v237
	v_mov_b32_e32 v144, v238
	v_mov_b32_e32 v145, v239
	v_lshl_add_u64 v[182:183], v[180:181], 2, s[4:5]
	v_mov_b32_e32 v190, v228
	v_mov_b32_e32 v138, v240
	v_mov_b32_e32 v139, v241
	v_mov_b32_e32 v140, v242
	v_mov_b32_e32 v141, v243
	v_mov_b32_e32 v134, v244
	v_mov_b32_e32 v135, v245
	v_mov_b32_e32 v136, v246
	v_mov_b32_e32 v137, v247
	s_nop 0
	v_mov_b32_e32 v130, v248
	v_mov_b32_e32 v131, v249
	v_mov_b32_e32 v132, v250
	v_mov_b32_e32 v133, v251
	v_or_b32_e32 v192, 16, v180
	v_ashrrev_i32_e32 v193, 31, v192
	v_lshl_add_u64 v[168:169], v[192:193], 2, s[4:5]
	v_mov_b32_e32 v194, v229
	v_or_b32_e32 v188, 32, v180
	v_or_b32_e32 v184, 48, v180
	v_mov_b64_e32 v[166:167], s[0:1]
	v_add_u32_e32 v178, 0x90, v180
	v_add_u32_e32 v174, 0xa0, v180
	v_add_u32_e32 v168, 0xb0, v180
	v_ashrrev_i32_e32 v189, 31, v188
	v_ashrrev_i32_e32 v185, 31, v184
	v_add_u32_e32 v193, 0x80, v180
	v_mad_i64_i32 v[196:197], s[18:19], v180, s56, v[166:167]
	v_ashrrev_i32_e32 v179, 31, v178
	v_ashrrev_i32_e32 v175, 31, v174
	v_ashrrev_i32_e32 v169, 31, v168
	v_lshl_add_u64 v[180:181], v[188:189], 2, s[4:5]
	v_lshl_add_u64 v[186:187], v[184:185], 2, s[4:5]
	v_lshl_add_u64 v[198:199], v[178:179], 2, s[4:5]
	v_lshl_add_u64 v[200:201], v[174:175], 2, s[4:5]
	v_lshl_add_u64 v[202:203], v[168:169], 2, s[4:5]
	v_mov_b32_e32 v204, v233
	s_nop 0
	v_mov_b32_e32 v186, v234
	s_nop 0
	v_mov_b32_e32 v180, v252
	s_nop 0
	v_mov_b32_e32 v182, v235
	s_lshl_b32 s16, s17, 7
	s_ashr_i32 s17, s16, 31
	s_lshl_b64 s[16:17], s[16:17], 1
	v_lshlrev_b32_e32 v154, 1, v156
	v_lshl_add_u64 v[196:197], v[196:197], 0, s[16:17]
	s_and_b64 vcc, exec, s[2:3]
	s_mov_b64 s[34:35], s[14:15]
	s_mov_b64 s[24:25], s[12:13]
	v_pk_fma_f32 v[118:119], v[118:119], v[190:191], v[138:139] op_sel_hi:[1,0,1]
	v_pk_fma_f32 v[126:127], v[126:127], v[190:191], v[142:143] op_sel_hi:[1,0,1]
	v_pk_fma_f32 v[128:129], v[128:129], v[190:191], v[144:145] op_sel_hi:[1,0,1]
	v_pk_fma_f32 v[122:123], v[122:123], v[190:191], v[134:135] op_sel_hi:[1,0,1]
	v_pk_fma_f32 v[124:125], v[124:125], v[190:191], v[136:137] op_sel_hi:[1,0,1]
	v_mul_f32_e32 v169, 0xbfb8aa3b, v126
	v_mul_f32_e32 v175, 0xbfb8aa3b, v127
	v_mul_f32_e32 v179, 0xbfb8aa3b, v128
	v_mul_f32_e32 v181, 0xbfb8aa3b, v129
	v_mul_f32_e32 v183, 0xbfb8aa3b, v122
	v_mul_f32_e32 v185, 0xbfb8aa3b, v123
	v_mul_f32_e32 v187, 0xbfb8aa3b, v124
	v_mul_f32_e32 v189, 0xbfb8aa3b, v125
	v_exp_f32_e32 v169, v169
	v_exp_f32_e32 v175, v175
	v_exp_f32_e32 v179, v179
	v_exp_f32_e32 v181, v181
	v_exp_f32_e32 v183, v183
	v_exp_f32_e32 v185, v185
	v_exp_f32_e32 v187, v187
	v_exp_f32_e32 v189, v189
	v_add_f32_e32 v169, 1.0, v169
	v_add_f32_e32 v175, 1.0, v175
	v_add_f32_e32 v179, 1.0, v179
	v_add_f32_e32 v181, 1.0, v181
	v_add_f32_e32 v183, 1.0, v183
	v_add_f32_e32 v185, 1.0, v185
	v_add_f32_e32 v187, 1.0, v187
	v_add_f32_e32 v189, 1.0, v189
	v_pk_fma_f32 v[120:121], v[120:121], v[190:191], v[140:141] op_sel_hi:[1,0,1]
	v_pk_fma_f32 v[114:115], v[114:115], v[190:191], v[130:131] op_sel_hi:[1,0,1]
	v_pk_fma_f32 v[116:117], v[116:117], v[190:191], v[132:133] op_sel_hi:[1,0,1]
	v_rcp_f32_e32 v190, v169
	v_rcp_f32_e32 v191, v175
	v_rcp_f32_e32 v198, v179
	v_rcp_f32_e32 v199, v181
	v_rcp_f32_e32 v200, v183
	v_rcp_f32_e32 v201, v185
	v_rcp_f32_e32 v202, v187
	v_rcp_f32_e32 v203, v189
	v_pk_mul_f32 v[126:127], v[126:127], v[190:191]
	v_pk_mul_f32 v[128:129], v[128:129], v[198:199]
	v_pk_mul_f32 v[122:123], v[122:123], v[200:201]
	v_pk_mul_f32 v[124:125], v[124:125], v[202:203]
	v_pk_mul_f32 v[118:119], v[118:119], v[126:127]
	v_pk_mul_f32 v[120:121], v[120:121], v[128:129]
	v_pk_mul_f32 v[122:123], v[114:115], v[122:123]
	v_pk_mul_f32 v[124:125], v[116:117], v[124:125]
	v_pk_fma_f32 v[110:111], v[110:111], v[194:195], v[142:143] op_sel_hi:[1,0,1]
	v_lshl_add_u64 v[126:127], v[196:197], 0, v[154:155]
	v_cvt_pk_bf16_f32 v114, v118, v119
	v_cvt_pk_bf16_f32 v115, v120, v121
	v_cvt_pk_bf16_f32 v116, v122, v123
	v_cvt_pk_bf16_f32 v117, v124, v125
	v_mul_f32_e32 v118, 0xbfb8aa3b, v110
	v_mul_f32_e32 v119, 0xbfb8aa3b, v111
	v_pk_fma_f32 v[112:113], v[112:113], v[194:195], v[144:145] op_sel_hi:[1,0,1]
	v_exp_f32_e32 v118, v118
	v_exp_f32_e32 v119, v119
	global_store_dwordx4 v[126:127], v[114:117], off nt
	v_pk_fma_f32 v[102:103], v[102:103], v[194:195], v[138:139] op_sel_hi:[1,0,1]
	v_pk_fma_f32 v[106:107], v[106:107], v[194:195], v[134:135] op_sel_hi:[1,0,1]
	v_mul_f32_e32 v116, 0xbfb8aa3b, v112
	v_mul_f32_e32 v117, 0xbfb8aa3b, v113
	v_exp_f32_e32 v116, v116
	v_exp_f32_e32 v117, v117
	v_add_f32_e32 v114, 1.0, v118
	v_add_f32_e32 v115, 1.0, v119
	v_rcp_f32_e32 v114, v114
	v_rcp_f32_e32 v115, v115
	v_add_f32_e32 v116, 1.0, v116
	v_add_f32_e32 v117, 1.0, v117
	v_rcp_f32_e32 v116, v116
	v_rcp_f32_e32 v117, v117
	v_pk_mul_f32 v[110:111], v[110:111], v[114:115]
	v_pk_fma_f32 v[104:105], v[104:105], v[194:195], v[140:141] op_sel_hi:[1,0,1]
	v_pk_mul_f32 v[102:103], v[102:103], v[110:111]
	v_pk_mul_f32 v[110:111], v[112:113], v[116:117]
	v_mul_f32_e32 v112, 0xbfb8aa3b, v106
	v_mul_f32_e32 v113, 0xbfb8aa3b, v107
	v_exp_f32_e32 v112, v112
	v_exp_f32_e32 v113, v113
	v_pk_fma_f32 v[108:109], v[108:109], v[194:195], v[136:137] op_sel_hi:[1,0,1]
	v_pk_mul_f32 v[104:105], v[104:105], v[110:111]
	v_add_f32_e32 v110, 1.0, v112
	v_add_f32_e32 v111, 1.0, v113
	v_mul_f32_e32 v112, 0xbfb8aa3b, v108
	v_mul_f32_e32 v113, 0xbfb8aa3b, v109
	v_exp_f32_e32 v112, v112
	v_exp_f32_e32 v113, v113
	v_rcp_f32_e32 v110, v110
	v_rcp_f32_e32 v111, v111
	v_add_f32_e32 v112, 1.0, v112
	v_add_f32_e32 v113, 1.0, v113
	v_rcp_f32_e32 v112, v112
	v_rcp_f32_e32 v113, v113
	v_pk_mul_f32 v[106:107], v[106:107], v[110:111]
	v_pk_fma_f32 v[98:99], v[98:99], v[194:195], v[130:131] op_sel_hi:[1,0,1]
	v_pk_fma_f32 v[100:101], v[100:101], v[194:195], v[132:133] op_sel_hi:[1,0,1]
	v_pk_mul_f32 v[106:107], v[98:99], v[106:107]
	v_pk_mul_f32 v[98:99], v[108:109], v[112:113]
	v_pk_fma_f32 v[94:95], v[94:95], v[204:205], v[142:143] op_sel_hi:[1,0,1]
	v_pk_mul_f32 v[108:109], v[100:101], v[98:99]
	v_mad_i64_i32 v[98:99], s[18:19], v192, s56, v[166:167]
	v_lshl_add_u64 v[98:99], v[98:99], 0, s[16:17]
	v_lshl_add_u64 v[110:111], v[98:99], 0, v[154:155]
	v_cvt_pk_bf16_f32 v98, v102, v103
	v_cvt_pk_bf16_f32 v99, v104, v105
	v_cvt_pk_bf16_f32 v100, v106, v107
	v_cvt_pk_bf16_f32 v101, v108, v109
	v_mul_f32_e32 v102, 0xbfb8aa3b, v94
	v_mul_f32_e32 v103, 0xbfb8aa3b, v95
	v_pk_fma_f32 v[96:97], v[96:97], v[204:205], v[144:145] op_sel_hi:[1,0,1]
	v_exp_f32_e32 v102, v102
	v_exp_f32_e32 v103, v103
	global_store_dwordx4 v[110:111], v[98:101], off nt
	v_pk_fma_f32 v[86:87], v[86:87], v[204:205], v[138:139] op_sel_hi:[1,0,1]
	v_pk_fma_f32 v[90:91], v[90:91], v[204:205], v[134:135] op_sel_hi:[1,0,1]
	v_mul_f32_e32 v100, 0xbfb8aa3b, v96
	v_mul_f32_e32 v101, 0xbfb8aa3b, v97
	v_exp_f32_e32 v100, v100
	v_exp_f32_e32 v101, v101
	v_add_f32_e32 v98, 1.0, v102
	v_add_f32_e32 v99, 1.0, v103
	v_rcp_f32_e32 v98, v98
	v_rcp_f32_e32 v99, v99
	v_add_f32_e32 v100, 1.0, v100
	v_add_f32_e32 v101, 1.0, v101
	v_rcp_f32_e32 v100, v100
	v_rcp_f32_e32 v101, v101
	v_pk_mul_f32 v[94:95], v[94:95], v[98:99]
	v_pk_fma_f32 v[88:89], v[88:89], v[204:205], v[140:141] op_sel_hi:[1,0,1]
	v_pk_mul_f32 v[86:87], v[86:87], v[94:95]
	v_pk_mul_f32 v[94:95], v[96:97], v[100:101]
	v_mul_f32_e32 v96, 0xbfb8aa3b, v90
	v_mul_f32_e32 v97, 0xbfb8aa3b, v91
	v_exp_f32_e32 v96, v96
	v_exp_f32_e32 v97, v97
	v_pk_fma_f32 v[92:93], v[92:93], v[204:205], v[136:137] op_sel_hi:[1,0,1]
	v_pk_mul_f32 v[88:89], v[88:89], v[94:95]
	v_add_f32_e32 v94, 1.0, v96
	v_add_f32_e32 v95, 1.0, v97
	v_mul_f32_e32 v96, 0xbfb8aa3b, v92
	v_mul_f32_e32 v97, 0xbfb8aa3b, v93
	v_exp_f32_e32 v96, v96
	v_exp_f32_e32 v97, v97
	v_rcp_f32_e32 v94, v94
	v_rcp_f32_e32 v95, v95
	v_add_f32_e32 v96, 1.0, v96
	v_add_f32_e32 v97, 1.0, v97
	v_rcp_f32_e32 v96, v96
	v_rcp_f32_e32 v97, v97
	v_pk_mul_f32 v[90:91], v[90:91], v[94:95]
	v_pk_fma_f32 v[82:83], v[82:83], v[204:205], v[130:131] op_sel_hi:[1,0,1]
	v_pk_fma_f32 v[84:85], v[84:85], v[204:205], v[132:133] op_sel_hi:[1,0,1]
	v_pk_mul_f32 v[90:91], v[82:83], v[90:91]
	v_pk_mul_f32 v[82:83], v[92:93], v[96:97]
	v_pk_fma_f32 v[78:79], v[78:79], v[186:187], v[142:143] op_sel_hi:[1,0,1]
	v_pk_mul_f32 v[92:93], v[84:85], v[82:83]
	v_mad_i64_i32 v[82:83], s[18:19], v188, s56, v[166:167]
	v_lshl_add_u64 v[82:83], v[82:83], 0, s[16:17]
	v_lshl_add_u64 v[94:95], v[82:83], 0, v[154:155]
	v_cvt_pk_bf16_f32 v82, v86, v87
	v_cvt_pk_bf16_f32 v83, v88, v89
	v_cvt_pk_bf16_f32 v84, v90, v91
	v_cvt_pk_bf16_f32 v85, v92, v93
	v_mul_f32_e32 v86, 0xbfb8aa3b, v78
	v_mul_f32_e32 v87, 0xbfb8aa3b, v79
	v_pk_fma_f32 v[80:81], v[80:81], v[186:187], v[144:145] op_sel_hi:[1,0,1]
	v_exp_f32_e32 v86, v86
	v_exp_f32_e32 v87, v87
	global_store_dwordx4 v[94:95], v[82:85], off nt
	v_pk_fma_f32 v[70:71], v[70:71], v[186:187], v[138:139] op_sel_hi:[1,0,1]
	v_pk_fma_f32 v[74:75], v[74:75], v[186:187], v[134:135] op_sel_hi:[1,0,1]
	v_mul_f32_e32 v84, 0xbfb8aa3b, v80
	v_mul_f32_e32 v85, 0xbfb8aa3b, v81
	v_exp_f32_e32 v84, v84
	v_exp_f32_e32 v85, v85
	v_add_f32_e32 v82, 1.0, v86
	v_add_f32_e32 v83, 1.0, v87
	v_rcp_f32_e32 v82, v82
	v_rcp_f32_e32 v83, v83
	v_add_f32_e32 v84, 1.0, v84
	v_add_f32_e32 v85, 1.0, v85
	v_rcp_f32_e32 v84, v84
	v_rcp_f32_e32 v85, v85
	v_pk_mul_f32 v[78:79], v[78:79], v[82:83]
	v_pk_fma_f32 v[72:73], v[72:73], v[186:187], v[140:141] op_sel_hi:[1,0,1]
	v_pk_mul_f32 v[70:71], v[70:71], v[78:79]
	v_pk_mul_f32 v[78:79], v[80:81], v[84:85]
	v_mul_f32_e32 v80, 0xbfb8aa3b, v74
	v_mul_f32_e32 v81, 0xbfb8aa3b, v75
	v_exp_f32_e32 v80, v80
	v_exp_f32_e32 v81, v81
	v_pk_fma_f32 v[76:77], v[76:77], v[186:187], v[136:137] op_sel_hi:[1,0,1]
	v_pk_mul_f32 v[72:73], v[72:73], v[78:79]
	v_add_f32_e32 v78, 1.0, v80
	v_add_f32_e32 v79, 1.0, v81
	v_mul_f32_e32 v80, 0xbfb8aa3b, v76
	v_mul_f32_e32 v81, 0xbfb8aa3b, v77
	v_exp_f32_e32 v80, v80
	v_exp_f32_e32 v81, v81
	v_rcp_f32_e32 v78, v78
	v_rcp_f32_e32 v79, v79
	v_add_f32_e32 v80, 1.0, v80
	v_add_f32_e32 v81, 1.0, v81
	v_rcp_f32_e32 v80, v80
	v_rcp_f32_e32 v81, v81
	v_pk_mul_f32 v[74:75], v[74:75], v[78:79]
	v_pk_fma_f32 v[66:67], v[66:67], v[186:187], v[130:131] op_sel_hi:[1,0,1]
	v_pk_fma_f32 v[68:69], v[68:69], v[186:187], v[132:133] op_sel_hi:[1,0,1]
	v_pk_mul_f32 v[74:75], v[66:67], v[74:75]
	v_pk_mul_f32 v[66:67], v[76:77], v[80:81]
	v_pk_fma_f32 v[62:63], v[62:63], v[182:183], v[142:143] op_sel_hi:[1,0,1]
	v_pk_mul_f32 v[76:77], v[68:69], v[66:67]
	v_mad_i64_i32 v[66:67], s[18:19], v184, s56, v[166:167]
	v_lshl_add_u64 v[66:67], v[66:67], 0, s[16:17]
	v_lshl_add_u64 v[78:79], v[66:67], 0, v[154:155]
	v_cvt_pk_bf16_f32 v66, v70, v71
	v_cvt_pk_bf16_f32 v67, v72, v73
	v_cvt_pk_bf16_f32 v68, v74, v75
	v_cvt_pk_bf16_f32 v69, v76, v77
	v_mul_f32_e32 v70, 0xbfb8aa3b, v62
	v_mul_f32_e32 v71, 0xbfb8aa3b, v63
	v_pk_fma_f32 v[64:65], v[64:65], v[182:183], v[144:145] op_sel_hi:[1,0,1]
	v_exp_f32_e32 v70, v70
	v_exp_f32_e32 v71, v71
	global_store_dwordx4 v[78:79], v[66:69], off nt
	v_pk_fma_f32 v[54:55], v[54:55], v[182:183], v[138:139] op_sel_hi:[1,0,1]
	v_pk_fma_f32 v[58:59], v[58:59], v[182:183], v[134:135] op_sel_hi:[1,0,1]
	v_mul_f32_e32 v68, 0xbfb8aa3b, v64
	v_mul_f32_e32 v69, 0xbfb8aa3b, v65
	v_exp_f32_e32 v68, v68
	v_exp_f32_e32 v69, v69
	v_add_f32_e32 v66, 1.0, v70
	v_add_f32_e32 v67, 1.0, v71
	v_rcp_f32_e32 v66, v66
	v_rcp_f32_e32 v67, v67
	v_add_f32_e32 v68, 1.0, v68
	v_add_f32_e32 v69, 1.0, v69
	v_rcp_f32_e32 v68, v68
	v_rcp_f32_e32 v69, v69
	v_pk_mul_f32 v[62:63], v[62:63], v[66:67]
	v_pk_fma_f32 v[56:57], v[56:57], v[182:183], v[140:141] op_sel_hi:[1,0,1]
	v_pk_mul_f32 v[54:55], v[54:55], v[62:63]
	v_pk_mul_f32 v[62:63], v[64:65], v[68:69]
	v_mul_f32_e32 v64, 0xbfb8aa3b, v58
	v_mul_f32_e32 v65, 0xbfb8aa3b, v59
	v_exp_f32_e32 v64, v64
	v_exp_f32_e32 v65, v65
	v_pk_fma_f32 v[60:61], v[60:61], v[182:183], v[136:137] op_sel_hi:[1,0,1]
	v_pk_mul_f32 v[56:57], v[56:57], v[62:63]
	v_add_f32_e32 v62, 1.0, v64
	v_add_f32_e32 v63, 1.0, v65
	v_mul_f32_e32 v64, 0xbfb8aa3b, v60
	v_mul_f32_e32 v65, 0xbfb8aa3b, v61
	v_exp_f32_e32 v64, v64
	v_exp_f32_e32 v65, v65
	v_rcp_f32_e32 v62, v62
	v_rcp_f32_e32 v63, v63
	v_add_f32_e32 v64, 1.0, v64
	v_add_f32_e32 v65, 1.0, v65
	v_rcp_f32_e32 v64, v64
	v_rcp_f32_e32 v65, v65
	v_pk_mul_f32 v[58:59], v[58:59], v[62:63]
	v_pk_fma_f32 v[50:51], v[50:51], v[182:183], v[130:131] op_sel_hi:[1,0,1]
	v_pk_fma_f32 v[52:53], v[52:53], v[182:183], v[132:133] op_sel_hi:[1,0,1]
	v_pk_mul_f32 v[58:59], v[50:51], v[58:59]
	v_pk_mul_f32 v[50:51], v[60:61], v[64:65]
	v_pk_fma_f32 v[46:47], v[46:47], v[180:181], v[142:143] op_sel_hi:[1,0,1]
	v_pk_mul_f32 v[60:61], v[52:53], v[50:51]
	v_mad_i64_i32 v[50:51], s[18:19], v193, s56, v[166:167]
	v_lshl_add_u64 v[50:51], v[50:51], 0, s[16:17]
	v_lshl_add_u64 v[62:63], v[50:51], 0, v[154:155]
	v_cvt_pk_bf16_f32 v50, v54, v55
	v_cvt_pk_bf16_f32 v51, v56, v57
	v_cvt_pk_bf16_f32 v52, v58, v59
	v_cvt_pk_bf16_f32 v53, v60, v61
	v_mul_f32_e32 v54, 0xbfb8aa3b, v46
	v_mul_f32_e32 v55, 0xbfb8aa3b, v47
	v_pk_fma_f32 v[48:49], v[48:49], v[180:181], v[144:145] op_sel_hi:[1,0,1]
	v_exp_f32_e32 v54, v54
	v_exp_f32_e32 v55, v55
	global_store_dwordx4 v[62:63], v[50:53], off nt
	v_pk_fma_f32 v[38:39], v[38:39], v[180:181], v[138:139] op_sel_hi:[1,0,1]
	v_pk_fma_f32 v[42:43], v[42:43], v[180:181], v[134:135] op_sel_hi:[1,0,1]
	v_mul_f32_e32 v52, 0xbfb8aa3b, v48
	v_mul_f32_e32 v53, 0xbfb8aa3b, v49
	v_exp_f32_e32 v52, v52
	v_exp_f32_e32 v53, v53
	v_add_f32_e32 v50, 1.0, v54
	v_add_f32_e32 v51, 1.0, v55
	v_rcp_f32_e32 v50, v50
	v_rcp_f32_e32 v51, v51
	v_add_f32_e32 v52, 1.0, v52
	v_add_f32_e32 v53, 1.0, v53
	v_rcp_f32_e32 v52, v52
	v_rcp_f32_e32 v53, v53
	v_pk_mul_f32 v[46:47], v[46:47], v[50:51]
	v_pk_fma_f32 v[40:41], v[40:41], v[180:181], v[140:141] op_sel_hi:[1,0,1]
	v_pk_mul_f32 v[38:39], v[38:39], v[46:47]
	v_pk_mul_f32 v[46:47], v[48:49], v[52:53]
	v_mul_f32_e32 v48, 0xbfb8aa3b, v42
	v_mul_f32_e32 v49, 0xbfb8aa3b, v43
	v_exp_f32_e32 v48, v48
	v_exp_f32_e32 v49, v49
	v_pk_fma_f32 v[44:45], v[44:45], v[180:181], v[136:137] op_sel_hi:[1,0,1]
	v_pk_mul_f32 v[40:41], v[40:41], v[46:47]
	v_add_f32_e32 v46, 1.0, v48
	v_add_f32_e32 v47, 1.0, v49
	v_mul_f32_e32 v48, 0xbfb8aa3b, v44
	v_mul_f32_e32 v49, 0xbfb8aa3b, v45
	v_exp_f32_e32 v48, v48
	v_exp_f32_e32 v49, v49
	v_rcp_f32_e32 v46, v46
	v_rcp_f32_e32 v47, v47
	v_add_f32_e32 v48, 1.0, v48
	v_add_f32_e32 v49, 1.0, v49
	v_rcp_f32_e32 v48, v48
	v_rcp_f32_e32 v49, v49
	v_pk_mul_f32 v[42:43], v[42:43], v[46:47]
	v_pk_fma_f32 v[34:35], v[34:35], v[180:181], v[130:131] op_sel_hi:[1,0,1]
	v_pk_fma_f32 v[36:37], v[36:37], v[180:181], v[132:133] op_sel_hi:[1,0,1]
	v_pk_mul_f32 v[42:43], v[34:35], v[42:43]
	v_pk_mul_f32 v[34:35], v[44:45], v[48:49]
	v_pk_fma_f32 v[30:31], v[30:31], v[176:177], v[142:143] op_sel_hi:[1,0,1]
	v_pk_mul_f32 v[44:45], v[36:37], v[34:35]
	v_mad_i64_i32 v[34:35], s[18:19], v178, s56, v[166:167]
	v_lshl_add_u64 v[34:35], v[34:35], 0, s[16:17]
	v_lshl_add_u64 v[46:47], v[34:35], 0, v[154:155]
	v_cvt_pk_bf16_f32 v34, v38, v39
	v_cvt_pk_bf16_f32 v35, v40, v41
	v_cvt_pk_bf16_f32 v36, v42, v43
	v_cvt_pk_bf16_f32 v37, v44, v45
	v_mul_f32_e32 v38, 0xbfb8aa3b, v30
	v_mul_f32_e32 v39, 0xbfb8aa3b, v31
	v_pk_fma_f32 v[32:33], v[32:33], v[176:177], v[144:145] op_sel_hi:[1,0,1]
	v_exp_f32_e32 v38, v38
	v_exp_f32_e32 v39, v39
	global_store_dwordx4 v[46:47], v[34:37], off nt
	v_pk_fma_f32 v[22:23], v[22:23], v[176:177], v[138:139] op_sel_hi:[1,0,1]
	v_pk_fma_f32 v[26:27], v[26:27], v[176:177], v[134:135] op_sel_hi:[1,0,1]
	v_mul_f32_e32 v36, 0xbfb8aa3b, v32
	v_mul_f32_e32 v37, 0xbfb8aa3b, v33
	v_exp_f32_e32 v36, v36
	v_exp_f32_e32 v37, v37
	v_add_f32_e32 v34, 1.0, v38
	v_add_f32_e32 v35, 1.0, v39
	v_rcp_f32_e32 v34, v34
	v_rcp_f32_e32 v35, v35
	v_add_f32_e32 v36, 1.0, v36
	v_add_f32_e32 v37, 1.0, v37
	v_rcp_f32_e32 v36, v36
	v_rcp_f32_e32 v37, v37
	v_pk_mul_f32 v[30:31], v[30:31], v[34:35]
	v_pk_fma_f32 v[24:25], v[24:25], v[176:177], v[140:141] op_sel_hi:[1,0,1]
	v_pk_mul_f32 v[22:23], v[22:23], v[30:31]
	v_pk_mul_f32 v[30:31], v[32:33], v[36:37]
	v_mul_f32_e32 v32, 0xbfb8aa3b, v26
	v_mul_f32_e32 v33, 0xbfb8aa3b, v27
	v_exp_f32_e32 v32, v32
	v_exp_f32_e32 v33, v33
	v_pk_fma_f32 v[28:29], v[28:29], v[176:177], v[136:137] op_sel_hi:[1,0,1]
	v_pk_mul_f32 v[24:25], v[24:25], v[30:31]
	v_add_f32_e32 v30, 1.0, v32
	v_add_f32_e32 v31, 1.0, v33
	v_mul_f32_e32 v32, 0xbfb8aa3b, v28
	v_mul_f32_e32 v33, 0xbfb8aa3b, v29
	v_exp_f32_e32 v32, v32
	v_exp_f32_e32 v33, v33
	v_rcp_f32_e32 v30, v30
	v_rcp_f32_e32 v31, v31
	v_add_f32_e32 v32, 1.0, v32
	v_add_f32_e32 v33, 1.0, v33
	v_rcp_f32_e32 v32, v32
	v_rcp_f32_e32 v33, v33
	v_pk_mul_f32 v[26:27], v[26:27], v[30:31]
	v_pk_fma_f32 v[18:19], v[18:19], v[176:177], v[130:131] op_sel_hi:[1,0,1]
	v_pk_fma_f32 v[20:21], v[20:21], v[176:177], v[132:133] op_sel_hi:[1,0,1]
	v_pk_mul_f32 v[26:27], v[18:19], v[26:27]
	v_pk_mul_f32 v[18:19], v[28:29], v[32:33]
	v_pk_fma_f32 v[14:15], v[14:15], v[172:173], v[142:143] op_sel_hi:[1,0,1]
	v_pk_mul_f32 v[28:29], v[20:21], v[18:19]
	v_mad_i64_i32 v[18:19], s[18:19], v174, s56, v[166:167]
	v_lshl_add_u64 v[18:19], v[18:19], 0, s[16:17]
	v_lshl_add_u64 v[30:31], v[18:19], 0, v[154:155]
	v_cvt_pk_bf16_f32 v18, v22, v23
	v_cvt_pk_bf16_f32 v19, v24, v25
	v_cvt_pk_bf16_f32 v20, v26, v27
	v_cvt_pk_bf16_f32 v21, v28, v29
	v_mul_f32_e32 v22, 0xbfb8aa3b, v14
	v_mul_f32_e32 v23, 0xbfb8aa3b, v15
	v_pk_fma_f32 v[16:17], v[16:17], v[172:173], v[144:145] op_sel_hi:[1,0,1]
	v_exp_f32_e32 v22, v22
	v_exp_f32_e32 v23, v23
	global_store_dwordx4 v[30:31], v[18:21], off nt
	v_pk_fma_f32 v[6:7], v[6:7], v[172:173], v[138:139] op_sel_hi:[1,0,1]
	v_pk_fma_f32 v[10:11], v[10:11], v[172:173], v[134:135] op_sel_hi:[1,0,1]
	v_mul_f32_e32 v20, 0xbfb8aa3b, v16
	v_mul_f32_e32 v21, 0xbfb8aa3b, v17
	v_exp_f32_e32 v20, v20
	v_exp_f32_e32 v21, v21
	v_add_f32_e32 v18, 1.0, v22
	v_add_f32_e32 v19, 1.0, v23
	v_rcp_f32_e32 v18, v18
	v_rcp_f32_e32 v19, v19
	v_add_f32_e32 v20, 1.0, v20
	v_add_f32_e32 v21, 1.0, v21
	v_rcp_f32_e32 v20, v20
	v_rcp_f32_e32 v21, v21
	v_pk_mul_f32 v[14:15], v[14:15], v[18:19]
	v_pk_fma_f32 v[8:9], v[8:9], v[172:173], v[140:141] op_sel_hi:[1,0,1]
	v_pk_mul_f32 v[6:7], v[6:7], v[14:15]
	v_pk_mul_f32 v[14:15], v[16:17], v[20:21]
	v_mul_f32_e32 v16, 0xbfb8aa3b, v10
	v_mul_f32_e32 v17, 0xbfb8aa3b, v11
	v_exp_f32_e32 v16, v16
	v_exp_f32_e32 v17, v17
	v_pk_fma_f32 v[12:13], v[12:13], v[172:173], v[136:137] op_sel_hi:[1,0,1]
	v_pk_mul_f32 v[8:9], v[8:9], v[14:15]
	v_add_f32_e32 v14, 1.0, v16
	v_add_f32_e32 v15, 1.0, v17
	v_mul_f32_e32 v16, 0xbfb8aa3b, v12
	v_mul_f32_e32 v17, 0xbfb8aa3b, v13
	v_exp_f32_e32 v16, v16
	v_exp_f32_e32 v17, v17
	v_rcp_f32_e32 v14, v14
	v_rcp_f32_e32 v15, v15
	v_add_f32_e32 v16, 1.0, v16
	v_add_f32_e32 v17, 1.0, v17
	v_rcp_f32_e32 v16, v16
	v_rcp_f32_e32 v17, v17
	v_pk_mul_f32 v[10:11], v[10:11], v[14:15]
	v_pk_fma_f32 v[2:3], v[2:3], v[172:173], v[130:131] op_sel_hi:[1,0,1]
	v_pk_fma_f32 v[4:5], v[4:5], v[172:173], v[132:133] op_sel_hi:[1,0,1]
	v_pk_mul_f32 v[10:11], v[2:3], v[10:11]
	v_pk_mul_f32 v[2:3], v[12:13], v[16:17]
	s_nop 0
	v_pk_mul_f32 v[12:13], v[4:5], v[2:3]
	v_mad_i64_i32 v[2:3], s[18:19], v168, s56, v[166:167]
	v_lshl_add_u64 v[2:3], v[2:3], 0, s[16:17]
	v_lshl_add_u64 v[14:15], v[2:3], 0, v[154:155]
	v_cvt_pk_bf16_f32 v2, v6, v7
	v_cvt_pk_bf16_f32 v3, v8, v9
	v_cvt_pk_bf16_f32 v4, v10, v11
	v_cvt_pk_bf16_f32 v5, v12, v13
	s_mov_b32 s17, s8
	s_mov_b32 s16, s10
	global_store_dwordx4 v[14:15], v[2:5], off nt
	s_cbranch_vccz .LBB0_3262
	s_waitcnt vmcnt(0)
	s_cmpk_gt_u32 s33, 0xff
	s_cbranch_scc1 .LBB0_3269
	s_barrier

	.amdhsa_kernel _Z10fwd_kernel6Params
		.amdhsa_group_segment_fixed_size 0
		.amdhsa_private_segment_fixed_size 0
		.amdhsa_kernarg_size 488
		.amdhsa_user_sgpr_count 2
		.amdhsa_user_sgpr_dispatch_ptr 0
		.amdhsa_user_sgpr_queue_ptr 0
		.amdhsa_user_sgpr_kernarg_segment_ptr 1
		.amdhsa_user_sgpr_dispatch_id 0
		.amdhsa_user_sgpr_kernarg_preload_length 0
		.amdhsa_user_sgpr_kernarg_preload_offset 0
		.amdhsa_user_sgpr_private_segment_size 0
		.amdhsa_uses_dynamic_stack 0
		.amdhsa_enable_private_segment 0
		.amdhsa_system_sgpr_workgroup_id_x 1
		.amdhsa_system_sgpr_workgroup_id_y 0
		.amdhsa_system_sgpr_workgroup_id_z 0
		.amdhsa_system_sgpr_workgroup_info 0
		.amdhsa_system_vgpr_workitem_id 2
		.amdhsa_next_free_vgpr 256
		.amdhsa_next_free_sgpr 98
		.amdhsa_accum_offset 256
		.amdhsa_reserve_vcc 1
		.amdhsa_float_round_mode_32 0
		.amdhsa_float_round_mode_16_64 0
		.amdhsa_float_denorm_mode_32 3
		.amdhsa_float_denorm_mode_16_64 3
		.amdhsa_dx10_clamp 1
		.amdhsa_ieee_mode 1
		.amdhsa_fp16_overflow 0
		.amdhsa_tg_split 0
		.amdhsa_exception_fp_ieee_invalid_op 0
		.amdhsa_exception_fp_denorm_src 0
		.amdhsa_exception_fp_ieee_div_zero 0
		.amdhsa_exception_fp_ieee_overflow 0
		.amdhsa_exception_fp_ieee_underflow 0
		.amdhsa_exception_fp_ieee_inexact 0
		.amdhsa_exception_int_div_zero 0
	.end_amdhsa_kernel

amdhsa.kernels:
  - .agpr_count:     0
    .args:
      - .offset:         0
        .size:           232
        .value_kind:     by_value
      - .offset:         232
        .size:           4
        .value_kind:     hidden_block_count_x
      - .offset:         236
        .size:           4
        .value_kind:     hidden_block_count_y
      - .offset:         240
        .size:           4
        .value_kind:     hidden_block_count_z
      - .offset:         244
        .size:           2
        .value_kind:     hidden_group_size_x
      - .offset:         246
        .size:           2
        .value_kind:     hidden_group_size_y
      - .offset:         248
        .size:           2
        .value_kind:     hidden_group_size_z
      - .offset:         250
        .size:           2
        .value_kind:     hidden_remainder_x
      - .offset:         252
        .size:           2
        .value_kind:     hidden_remainder_y
      - .offset:         254
        .size:           2
        .value_kind:     hidden_remainder_z
      - .offset:         272
        .size:           8
        .value_kind:     hidden_global_offset_x
      - .offset:         280
        .size:           8
        .value_kind:     hidden_global_offset_y
      - .offset:         288
        .size:           8
        .value_kind:     hidden_global_offset_z
      - .offset:         296
        .size:           2
        .value_kind:     hidden_grid_dims
      - .offset:         320
        .size:           8
        .value_kind:     hidden_multigrid_sync_arg
      - .offset:         352
        .size:           4
        .value_kind:     hidden_dynamic_lds_size
    .group_segment_fixed_size: 0
    .kernarg_segment_align: 8
    .kernarg_segment_size: 488
    .language:       OpenCL C
    .language_version:
      - 2
      - 0
    .max_flat_workgroup_size: 512
    .name:           _Z10fwd_kernel6Params
    .private_segment_fixed_size: 0
    .sgpr_count:     104
    .sgpr_spill_count: 34
    .symbol:         _Z10fwd_kernel6Params.kd
    .uniform_work_group_size: 1
    .uses_dynamic_stack: false
    .vgpr_count:     256
    .vgpr_spill_count: 0
    .wavefront_size: 64
